# baseline (speedup 1.0000x reference)
; __device__ __forceinline__ void finishSM(f32x16& p0, f32x16& p1, float alpha, float& l_reg, bf16x8& pa0, bf16x8& pa1, bf16x8& pa2, bf16x8& pa3) {
; #pragma unroll
;   for (int r = 0; r < 16; ++r) p1[r] = __builtin_amdgcn_exp2f(p1[r]);
;   float ps = 0;
; #pragma unroll
;   for (int r = 0; r < 16; ++r) ps += p0[r];
; #pragma unroll
;   for (int r = 0; r < 16; ++r) ps += p1[r];
;   { auto rr = __builtin_amdgcn_permlane32_swap(__float_as_uint(ps), __float_as_uint(ps), false, false);
;     ps = __uint_as_float(rr[0]) + __uint_as_float(rr[1]); }
;   l_reg = l_reg * alpha + ps;
;     ...
;   PK4(p0, 0, pa0); PK4(p0, 8, pa1); PK4(p1, 0, pa2); PK4(p1, 8, pa3);
;     ...
; }
; #pragma unroll
;   for (int r = 0; r < 16; ++r) { p0[r] = init; p1[r] = init; }
; #pragma unroll
;   for (int d0 = 0; d0 < 8; ++d0) { int cb = (d0 * 16 + hi * 8) * 2;
;     bf16x8 b0 = *reinterpret_cast<const bf16x8*>((const char*)Ks + KSWZ(r32, cb));
;     bf16x8 b1 = *reinterpret_cast<const bf16x8*>((const char*)Ks + KSWZ(32 + r32, cb));
;     p0 = __builtin_amdgcn_mfma_f32_32x32x16_bf16(b0, qr[d0], p0, 0, 0, 0);
;     p1 = __builtin_amdgcn_mfma_f32_32x32x16_bf16(b1, qr[d0], p1, 0, 0, 0); }
; }
; __device__ __forceinline__ void qkt_c(f32x16& p0, f32x16& p1, const bf16* Ks, const bf16x8* qr, int r32, int hi) {
;   const f32x16 cinit = {};
; #pragma unroll
;   for (int d0 = 0; d0 < 8; ++d0) { int cb = (d0 * 16 + hi * 8) * 2;
;     bf16x8 b0 = *reinterpret_cast<const bf16x8*>((const char*)Ks + KSWZ(r32, cb));
;     bf16x8 b1 = *reinterpret_cast<const bf16x8*>((const char*)Ks + KSWZ(32 + r32, cb));
;     p0 = __builtin_amdgcn_mfma_f32_32x32x16_bf16(b0, qr[d0], d0 == 0 ? cinit : p0, 0, 0, 0);
;     p1 = __builtin_amdgcn_mfma_f32_32x32x16_bf16(b1, qr[d0], d0 == 0 ? cinit : p1, 0, 0, 0); }
; }
.LBB0_118:
	s_add_i32 s2, s2, 2
	v_exp_f32_e32 v10, v88
	v_exp_f32_e32 v11, v89
	v_exp_f32_e32 v12, v90
	s_waitcnt lgkmcnt(1)
	v_mfma_f32_32x32x16_bf16 v[112:127], v[2:5], v[156:159], 0
	v_exp_f32_e32 v13, v91
	v_exp_f32_e32 v176, v92
	v_exp_f32_e32 v177, v93
	s_waitcnt lgkmcnt(0)
	v_mfma_f32_32x32x16_bf16 v[96:111], v[6:9], v[156:159], 0
	ds_read_b128 v[2:5], v201 offset:49152
	ds_read_b128 v[6:9], v201 offset:57344
	v_exp_f32_e32 v178, v94
	v_exp_f32_e32 v95, v95
	v_cvt_pk_bf16_f32 v92, v10, v11
	v_cvt_pk_bf16_f32 v93, v12, v13
	s_waitcnt lgkmcnt(1)
	v_mfma_f32_32x32x16_bf16 v[112:127], v[2:5], v[152:155], v[112:127]
	v_cvt_pk_bf16_f32 v94, v176, v177
	s_nop 1
	v_permlane32_swap_b32_e32 v92, v94
	v_exp_f32_e32 v251, v80
	v_add_f32_e32 v192, 0, v223
	v_add_f32_e32 v192, v225, v192
	s_waitcnt lgkmcnt(0)
	v_mfma_f32_32x32x16_bf16 v[96:111], v[6:9], v[152:155], v[96:111]
	ds_read_b128 v[2:5], v202 offset:49152
	ds_read_b128 v[6:9], v202 offset:57344
	v_add_f32_e32 v192, v221, v192
	v_add_f32_e32 v192, v224, v192
	v_add_f32_e32 v192, v220, v192
	v_add_f32_e32 v192, v222, v192
	v_add_f32_e32 v192, v218, v192
	v_add_f32_e32 v192, v219, v192
	s_waitcnt lgkmcnt(1)
	v_mfma_f32_32x32x16_bf16 v[112:127], v[2:5], v[148:151], v[112:127]
	v_add_f32_e32 v192, v215, v192
	v_add_f32_e32 v192, v217, v192
	v_add_f32_e32 v192, v214, v192
	v_add_f32_e32 v192, v216, v192
	v_add_f32_e32 v192, v210, v192
	s_waitcnt lgkmcnt(0)
	v_mfma_f32_32x32x16_bf16 v[96:111], v[6:9], v[148:151], v[96:111]
	ds_read_b128 v[2:5], v203 offset:49152
	ds_read_b128 v[6:9], v203 offset:57344
	v_add_u32_e32 v254, vcc_lo, v184
	v_add_u32_e32 v255, vcc_lo, v185
	s_waitcnt vmcnt(0)
	ds_write_b128 v254, v[160:163]
	v_exp_f32_e32 v252, v81
	v_add_f32_e32 v192, v213, v192
	v_exp_f32_e32 v253, v82
	v_add_f32_e32 v192, v211, v192
	s_waitcnt lgkmcnt(2)
	v_mfma_f32_32x32x16_bf16 v[112:127], v[2:5], v[144:147], v[112:127]
	v_exp_f32_e32 v186, v83
	v_add_f32_e32 v192, v212, v192
	v_exp_f32_e32 v188, v84
	v_add_f32_e32 v192, v251, v192
	s_waitcnt lgkmcnt(1)
	v_mfma_f32_32x32x16_bf16 v[96:111], v[6:9], v[144:147], v[96:111]
	ds_read_b128 v[2:5], v206 offset:49152
	ds_read_b128 v[6:9], v206 offset:57344
	ds_write_b128 v255, v[164:167]
	v_exp_f32_e32 v189, v85
	v_add_f32_e32 v192, v252, v192
	v_exp_f32_e32 v190, v86
	v_add_f32_e32 v192, v253, v192
	s_waitcnt lgkmcnt(2)
	v_mfma_f32_32x32x16_bf16 v[112:127], v[2:5], v[140:143], v[112:127]
	v_exp_f32_e32 v191, v87
	v_add_f32_e32 v192, v186, v192
	v_add_f32_e32 v192, v188, v192
	v_add_f32_e32 v192, v189, v192
	v_add_f32_e32 v192, v190, v192
	v_add_f32_e32 v192, v191, v192
	s_waitcnt lgkmcnt(1)
	v_mfma_f32_32x32x16_bf16 v[96:111], v[6:9], v[140:143], v[96:111]
	ds_read_b128 v[2:5], v204 offset:49152
	ds_read_b128 v[6:9], v204 offset:57344
	ds_write_b128 v198, v[168:171] offset:32768
	v_add_f32_e32 v192, v10, v192
	v_add_f32_e32 v192, v11, v192
	v_add_f32_e32 v192, v12, v192
	v_add_f32_e32 v192, v13, v192
	v_add_f32_e32 v192, v176, v192
	v_add_f32_e32 v192, v177, v192
	s_waitcnt lgkmcnt(2)
	v_mfma_f32_32x32x16_bf16 v[112:127], v[2:5], v[136:139], v[112:127]
	v_add_f32_e32 v192, v178, v192
	v_add_f32_e32 v192, v95, v192
	v_mov_b32_e32 v193, v192
	s_nop 1
	v_permlane32_swap_b32_e32 v192, v193
	v_add_f32_e32 v192, v192, v193
	s_waitcnt lgkmcnt(1)
	v_mfma_f32_32x32x16_bf16 v[96:111], v[6:9], v[136:139], v[96:111]
	ds_read_b128 v[2:5], v205 offset:49152
	ds_read_b128 v[6:9], v205 offset:57344
	ds_write_b128 v199, v[172:175] offset:32768
	v_add_f32_e32 v226, v183, v192
	v_cvt_pk_bf16_f32 v80, v223, v225
	v_cvt_pk_bf16_f32 v81, v221, v224
	v_cvt_pk_bf16_f32 v82, v220, v222
	v_cvt_pk_bf16_f32 v83, v218, v219
	v_cvt_pk_bf16_f32 v84, v215, v217
	s_waitcnt lgkmcnt(2)
	v_mfma_f32_32x32x16_bf16 v[112:127], v[2:5], v[132:135], v[112:127]
	v_cvt_pk_bf16_f32 v85, v214, v216
	v_cvt_pk_bf16_f32 v86, v210, v213
	v_cvt_pk_bf16_f32 v87, v211, v212
	v_cvt_pk_bf16_f32 v88, v251, v252
	v_cvt_pk_bf16_f32 v89, v253, v186
	v_cvt_pk_bf16_f32 v90, v188, v189
	s_waitcnt lgkmcnt(1)
	v_mfma_f32_32x32x16_bf16 v[96:111], v[6:9], v[132:135], v[96:111]
	ds_read_b128 v[2:5], v207 offset:49152
	ds_read_b128 v[6:9], v207 offset:57344
	v_cvt_pk_bf16_f32 v91, v190, v191
	v_cvt_pk_bf16_f32 v95, v178, v95
	v_permlane32_swap_b32_e32 v80, v82
	v_permlane32_swap_b32_e32 v81, v83
	v_permlane32_swap_b32_e32 v84, v86
	s_waitcnt lgkmcnt(1)
	v_mfma_f32_32x32x16_bf16 v[112:127], v[2:5], v[128:131], v[112:127]
	v_permlane32_swap_b32_e32 v85, v87
	v_permlane32_swap_b32_e32 v88, v90
	v_permlane32_swap_b32_e32 v89, v91
	v_permlane32_swap_b32_e32 v93, v95
	s_waitcnt lgkmcnt(0)
	v_mfma_f32_32x32x16_bf16 v[96:111], v[6:9], v[128:131], v[96:111]
	s_add_i32 s100, s2, 2
	s_mul_i32 s100, s100, 0x60000
	v_add_u32_e32 v254, s100, v14
	v_add_u32_e32 v255, s100, v15
	global_load_dwordx4 v[2:5], v254, s[58:59]
	global_load_dwordx4 v[6:9], v255, s[58:59]
	global_load_dwordx4 v[10:13], v254, s[8:9]
	global_load_dwordx4 v[176:179], v255, s[8:9]
	v_add_u32_e32 v255, vcc_hi, v208
	ds_read_b64_tr_b16 v[210:211], v255 offset:0
	ds_read_b64_tr_b16 v[212:213], v255 offset:0x800
	ds_read_b64_tr_b16 v[214:215], v255 offset:0x1000
	ds_read_b64_tr_b16 v[216:217], v255 offset:0x1800
	ds_read_b64_tr_b16 v[218:219], v255 offset:0x2000
	ds_read_b64_tr_b16 v[220:221], v255 offset:0x2800
	ds_read_b64_tr_b16 v[222:223], v255 offset:0x3000
	ds_read_b64_tr_b16 v[224:225], v255 offset:0x3800
	s_waitcnt lgkmcnt(0)
; #define SBAR() __builtin_amdgcn_sched_barrier(0)
; #define SWAIT() asm volatile("s_waitcnt vmcnt(4)" ::: "memory")
; #define RESC(a) do { if (!FIXED && __any((a) < 1.f)) { if (hi == 0) al_l[r32] = (a); asm volatile("s_waitcnt lgkmcnt(0)" ::: "memory"); \
;     _Pragma("unroll") for (int d = 0; d < 4; ++d) _Pragma("unroll") for (int r = 0; r < 16; ++r) o[d][r] *= al_l[crow(r, hi)]; } } while (0)
; #define MASK(P0, P1, t) do { if (BANDED) band_mask(P0, P1, rel00 + (t) * KVBLK, mlo, mhi); } while (0)
; template <int D0> __device__ __forceinline__ void pv_one(f32x16& od, int vb, bf16x8 pa0, bf16x8 pa1, bf16x8 pa2, bf16x8 pa3) {
;   const s16x4 l0 = tr_read<v_rd_off(D0, 0, 0)>(vb), h0 = tr_read<v_rd_off(D0, 0, 1)>(vb), l1 = tr_read<v_rd_off(D0, 1, 0)>(vb), h1 = tr_read<v_rd_off(D0, 1, 1)>(vb);
;   const s16x4 l2 = tr_read<v_rd_off(D0, 2, 0)>(vb), h2 = tr_read<v_rd_off(D0, 2, 1)>(vb), l3 = tr_read<v_rd_off(D0, 3, 0)>(vb), h3 = tr_read<v_rd_off(D0, 3, 1)>(vb);
;   asm volatile("s_waitcnt lgkmcnt(0)" ::: "memory"); SBAR();
;     ...
;   od = __builtin_amdgcn_mfma_f32_32x32x16_bf16(pa0, PK(l0, h0), od, 0, 0, 0);
;   od = __builtin_amdgcn_mfma_f32_32x32x16_bf16(pa1, PK(l1, h1), od, 0, 0, 0);
;   od = __builtin_amdgcn_mfma_f32_32x32x16_bf16(pa2, PK(l2, h2), od, 0, 0, 0);
;   od = __builtin_amdgcn_mfma_f32_32x32x16_bf16(pa3, PK(l3, h3), od, 0, 0, 0);
;     ...
; }
; __device__ __forceinline__ void pv_d0(f32x16* o, int vb, bf16x8 pa0, bf16x8 pa1, bf16x8 pa2, bf16x8 pa3) {
;   pv_one<0>(o[0], vb, pa0, pa1, pa2, pa3); pv_one<1>(o[1], vb, pa0, pa1, pa2, pa3); pv_one<2>(o[2], vb, pa0, pa1, pa2, pa3); pv_one<3>(o[3], vb, pa0, pa1, pa2, pa3);
; template <bool BANDED, bool FIXED> ...
;     ...
;     pv_d0(o, vb0, pa0, pa1, pa2, pa3); partialSM<FIXED, !BANDED>(pB0, pB1, m_reg, mnB, alB);
;     __syncthreads(); SWAIT(); SWRITE(0, SE);
;     RESC(alB); __syncthreads();
;     SBAR(); if (FIXED) qkt_c(pA0, pA1, K_lds, qr, r32, hi); else qkt(pA0, pA1, K_lds, qr, r32, hi, 0.f); MASK(pA0, pA1, j + 1);
;     finishSM(pB0, pB1, alB, l_reg, pa0, pa1, pa2, pa3); SBAR();
	s_nop 0
	v_mfma_f32_32x32x16_bf16 v[16:31], v[80:83], v[210:213], v[16:31]
	ds_read_b64_tr_b16 v[210:211], v255 offset:0x200
	ds_read_b64_tr_b16 v[212:213], v255 offset:0xa00
	v_mfma_f32_32x32x16_bf16 v[16:31], v[84:87], v[214:217], v[16:31]
	ds_read_b64_tr_b16 v[214:215], v255 offset:0x1200
	ds_read_b64_tr_b16 v[216:217], v255 offset:0x1a00
	v_mfma_f32_32x32x16_bf16 v[16:31], v[88:91], v[218:221], v[16:31]
	ds_read_b64_tr_b16 v[218:219], v255 offset:0x2200
	ds_read_b64_tr_b16 v[220:221], v255 offset:0x2a00
	v_mfma_f32_32x32x16_bf16 v[16:31], v[92:95], v[222:225], v[16:31]
	ds_read_b64_tr_b16 v[222:223], v255 offset:0x3200
	ds_read_b64_tr_b16 v[224:225], v255 offset:0x3a00
	s_waitcnt lgkmcnt(0)
	v_mfma_f32_32x32x16_bf16 v[32:47], v[80:83], v[210:213], v[32:47]
	ds_read_b64_tr_b16 v[210:211], v255 offset:0x400
	ds_read_b64_tr_b16 v[212:213], v255 offset:0xc00
	v_mfma_f32_32x32x16_bf16 v[32:47], v[84:87], v[214:217], v[32:47]
	ds_read_b64_tr_b16 v[214:215], v255 offset:0x1400
	ds_read_b64_tr_b16 v[216:217], v255 offset:0x1c00
	v_mfma_f32_32x32x16_bf16 v[32:47], v[88:91], v[218:221], v[32:47]
	ds_read_b64_tr_b16 v[218:219], v255 offset:0x2400
	ds_read_b64_tr_b16 v[220:221], v255 offset:0x2c00
	v_mfma_f32_32x32x16_bf16 v[32:47], v[92:95], v[222:225], v[32:47]
	ds_read_b64_tr_b16 v[222:223], v255 offset:0x3400
	ds_read_b64_tr_b16 v[224:225], v255 offset:0x3c00
	s_waitcnt lgkmcnt(0)
	v_mfma_f32_32x32x16_bf16 v[48:63], v[80:83], v[210:213], v[48:63]
	ds_read_b64_tr_b16 v[210:211], v255 offset:0x600
	ds_read_b64_tr_b16 v[212:213], v255 offset:0xe00
	v_mfma_f32_32x32x16_bf16 v[48:63], v[84:87], v[214:217], v[48:63]
	ds_read_b64_tr_b16 v[214:215], v255 offset:0x1600
	ds_read_b64_tr_b16 v[216:217], v255 offset:0x1e00
	v_mfma_f32_32x32x16_bf16 v[48:63], v[88:91], v[218:221], v[48:63]
	ds_read_b64_tr_b16 v[218:219], v255 offset:0x2600
	ds_read_b64_tr_b16 v[220:221], v255 offset:0x2e00
	v_mfma_f32_32x32x16_bf16 v[48:63], v[92:95], v[222:225], v[48:63]
	ds_read_b64_tr_b16 v[222:223], v255 offset:0x3600
	ds_read_b64_tr_b16 v[224:225], v255 offset:0x3e00
	s_waitcnt lgkmcnt(0)
	v_mfma_f32_32x32x16_bf16 v[64:79], v[80:83], v[210:213], v[64:79]
	v_exp_f32_e32 v210, v112
	v_exp_f32_e32 v211, v113
	v_exp_f32_e32 v212, v114
	v_exp_f32_e32 v213, v115
	v_mfma_f32_32x32x16_bf16 v[64:79], v[84:87], v[214:217], v[64:79]
	v_exp_f32_e32 v214, v116
	v_exp_f32_e32 v215, v117
	v_exp_f32_e32 v216, v118
	v_exp_f32_e32 v217, v119
	v_mfma_f32_32x32x16_bf16 v[64:79], v[88:91], v[218:221], v[64:79]
	v_exp_f32_e32 v218, v120
	v_exp_f32_e32 v219, v121
	v_exp_f32_e32 v220, v122
	v_exp_f32_e32 v221, v123
	s_mov_b32 s100, vcc_lo
	s_mov_b32 vcc_lo, vcc_hi
	s_mov_b32 vcc_hi, s101
	s_mov_b32 s101, s100
	s_waitcnt lgkmcnt(0)
	s_barrier
	ds_read_b128 v[80:83], v200 offset:32768
	ds_read_b128 v[84:87], v200 offset:40960
	v_mfma_f32_32x32x16_bf16 v[64:79], v[92:95], v[222:225], v[64:79]
	ds_read_b128 v[160:163], v201 offset:32768
	ds_read_b128 v[164:167], v201 offset:40960
	v_exp_f32_e32 v222, v124
	v_exp_f32_e32 v223, v125
	v_exp_f32_e32 v224, v126
	v_exp_f32_e32 v225, v127
	v_exp_f32_e32 v168, v104
	v_exp_f32_e32 v169, v105
	v_exp_f32_e32 v170, v106
	s_waitcnt lgkmcnt(3)
	v_mfma_f32_32x32x16_bf16 v[112:127], v[80:83], v[156:159], 0
	v_exp_f32_e32 v171, v107
	v_exp_f32_e32 v172, v108
	v_exp_f32_e32 v173, v109
	s_waitcnt lgkmcnt(2)
	v_mfma_f32_32x32x16_bf16 v[80:95], v[84:87], v[156:159], 0
	v_exp_f32_e32 v174, v110
	v_exp_f32_e32 v111, v111
	v_cvt_pk_bf16_f32 v108, v168, v169
	v_cvt_pk_bf16_f32 v109, v170, v171
	s_waitcnt lgkmcnt(1)
	v_mfma_f32_32x32x16_bf16 v[112:127], v[160:163], v[152:155], v[112:127]
	v_cvt_pk_bf16_f32 v110, v172, v173
	s_nop 1
	v_permlane32_swap_b32_e32 v108, v110
	v_exp_f32_e32 v251, v96
	v_add_f32_e32 v192, 0, v210
	v_add_f32_e32 v192, v211, v192
	s_waitcnt lgkmcnt(0)
	v_mfma_f32_32x32x16_bf16 v[80:95], v[164:167], v[152:155], v[80:95]
	ds_read_b128 v[160:163], v202 offset:32768
	ds_read_b128 v[164:167], v202 offset:40960
	v_add_f32_e32 v192, v212, v192
	v_add_f32_e32 v192, v213, v192
	v_add_f32_e32 v192, v214, v192
	v_add_f32_e32 v192, v215, v192
	v_add_f32_e32 v192, v216, v192
	v_add_f32_e32 v192, v217, v192
	s_waitcnt lgkmcnt(1)
	v_mfma_f32_32x32x16_bf16 v[112:127], v[160:163], v[148:151], v[112:127]
	v_add_f32_e32 v192, v218, v192
	v_add_f32_e32 v192, v219, v192
	v_add_f32_e32 v192, v220, v192
	v_add_f32_e32 v192, v221, v192
	v_add_f32_e32 v192, v222, v192
	s_waitcnt lgkmcnt(0)
	v_mfma_f32_32x32x16_bf16 v[80:95], v[164:167], v[148:151], v[80:95]
	ds_read_b128 v[160:163], v203 offset:32768
	ds_read_b128 v[164:167], v203 offset:40960
	v_add_u32_e32 v254, vcc_lo, v184
	v_add_u32_e32 v255, vcc_lo, v185
	s_waitcnt vmcnt(0)
	ds_write_b128 v254, v[2:5]
	v_exp_f32_e32 v252, v97
	v_add_f32_e32 v192, v223, v192
	v_exp_f32_e32 v253, v98
	v_add_f32_e32 v192, v224, v192
	s_waitcnt lgkmcnt(2)
	v_mfma_f32_32x32x16_bf16 v[112:127], v[160:163], v[144:147], v[112:127]
	v_exp_f32_e32 v186, v99
	v_add_f32_e32 v192, v225, v192
	v_exp_f32_e32 v188, v100
	v_add_f32_e32 v192, v251, v192
	s_waitcnt lgkmcnt(1)
	v_mfma_f32_32x32x16_bf16 v[80:95], v[164:167], v[144:147], v[80:95]
	ds_read_b128 v[160:163], v206 offset:32768
	ds_read_b128 v[164:167], v206 offset:40960
	ds_write_b128 v255, v[6:9]
	v_exp_f32_e32 v189, v101
	v_add_f32_e32 v192, v252, v192
	v_exp_f32_e32 v190, v102
	v_add_f32_e32 v192, v253, v192
	s_waitcnt lgkmcnt(2)
	v_mfma_f32_32x32x16_bf16 v[112:127], v[160:163], v[140:143], v[112:127]
	v_exp_f32_e32 v191, v103
	v_add_f32_e32 v192, v186, v192
	v_add_f32_e32 v192, v188, v192
	v_add_f32_e32 v192, v189, v192
	v_add_f32_e32 v192, v190, v192
	v_add_f32_e32 v192, v191, v192
	s_waitcnt lgkmcnt(1)
; __device__ __forceinline__ void finishSM(f32x16& p0, f32x16& p1, float alpha, float& l_reg, bf16x8& pa0, bf16x8& pa1, bf16x8& pa2, bf16x8& pa3) {
; #pragma unroll
;   for (int r = 0; r < 16; ++r) p1[r] = __builtin_amdgcn_exp2f(p1[r]);
;   float ps = 0;
; #pragma unroll
;   for (int r = 0; r < 16; ++r) ps += p0[r];
; #pragma unroll
;   for (int r = 0; r < 16; ++r) ps += p1[r];
;   { auto rr = __builtin_amdgcn_permlane32_swap(__float_as_uint(ps), __float_as_uint(ps), false, false);
;     ps = __uint_as_float(rr[0]) + __uint_as_float(rr[1]); }
;   l_reg = l_reg * alpha + ps;
;     ...
;   PK4(p0, 0, pa0); PK4(p0, 8, pa1); PK4(p1, 0, pa2); PK4(p1, 8, pa3);
;     ...
; }
; #pragma unroll
;   for (int r = 0; r < 16; ++r) { p0[r] = init; p1[r] = init; }
; #pragma unroll
;   for (int d0 = 0; d0 < 8; ++d0) { int cb = (d0 * 16 + hi * 8) * 2;
;     bf16x8 b0 = *reinterpret_cast<const bf16x8*>((const char*)Ks + KSWZ(r32, cb));
;     bf16x8 b1 = *reinterpret_cast<const bf16x8*>((const char*)Ks + KSWZ(32 + r32, cb));
;     p0 = __builtin_amdgcn_mfma_f32_32x32x16_bf16(b0, qr[d0], p0, 0, 0, 0);
;     p1 = __builtin_amdgcn_mfma_f32_32x32x16_bf16(b1, qr[d0], p1, 0, 0, 0); }
; }
; __device__ __forceinline__ void qkt_c(f32x16& p0, f32x16& p1, const bf16* Ks, const bf16x8* qr, int r32, int hi) {
;   const f32x16 cinit = {};
; #pragma unroll
;   for (int d0 = 0; d0 < 8; ++d0) { int cb = (d0 * 16 + hi * 8) * 2;
;     bf16x8 b0 = *reinterpret_cast<const bf16x8*>((const char*)Ks + KSWZ(r32, cb));
;     bf16x8 b1 = *reinterpret_cast<const bf16x8*>((const char*)Ks + KSWZ(32 + r32, cb));
;     p0 = __builtin_amdgcn_mfma_f32_32x32x16_bf16(b0, qr[d0], d0 == 0 ? cinit : p0, 0, 0, 0);
;     p1 = __builtin_amdgcn_mfma_f32_32x32x16_bf16(b1, qr[d0], d0 == 0 ? cinit : p1, 0, 0, 0); }
; }
; template <int D0> __device__ __forceinline__ void pv_one(f32x16& od, int vb, bf16x8 pa0, bf16x8 pa1, bf16x8 pa2, bf16x8 pa3) {
;   const s16x4 l0 = tr_read<v_rd_off(D0, 0, 0)>(vb), h0 = tr_read<v_rd_off(D0, 0, 1)>(vb), l1 = tr_read<v_rd_off(D0, 1, 0)>(vb), h1 = tr_read<v_rd_off(D0, 1, 1)>(vb);
;   const s16x4 l2 = tr_read<v_rd_off(D0, 2, 0)>(vb), h2 = tr_read<v_rd_off(D0, 2, 1)>(vb), l3 = tr_read<v_rd_off(D0, 3, 0)>(vb), h3 = tr_read<v_rd_off(D0, 3, 1)>(vb);
;   asm volatile("s_waitcnt lgkmcnt(0)" ::: "memory"); SBAR();
;     ...
;   od = __builtin_amdgcn_mfma_f32_32x32x16_bf16(pa0, PK(l0, h0), od, 0, 0, 0);
	v_mfma_f32_32x32x16_bf16 v[80:95], v[164:167], v[140:143], v[80:95]
	ds_read_b128 v[160:163], v204 offset:32768
	ds_read_b128 v[164:167], v204 offset:40960
	ds_write_b128 v198, v[10:13] offset:49152
	v_add_f32_e32 v192, v168, v192
	v_add_f32_e32 v192, v169, v192
	v_add_f32_e32 v192, v170, v192
	v_add_f32_e32 v192, v171, v192
	v_add_f32_e32 v192, v172, v192
	v_add_f32_e32 v192, v173, v192
	s_waitcnt lgkmcnt(2)
	v_mfma_f32_32x32x16_bf16 v[112:127], v[160:163], v[136:139], v[112:127]
	v_add_f32_e32 v192, v174, v192
	v_add_f32_e32 v192, v111, v192
	v_mov_b32_e32 v193, v192
	s_nop 1
	v_permlane32_swap_b32_e32 v192, v193
	v_add_f32_e32 v192, v192, v193
	s_waitcnt lgkmcnt(1)
	v_mfma_f32_32x32x16_bf16 v[80:95], v[164:167], v[136:139], v[80:95]
	ds_read_b128 v[160:163], v205 offset:32768
	ds_read_b128 v[164:167], v205 offset:40960
	ds_write_b128 v199, v[176:179] offset:49152
	v_add_f32_e32 v183, v226, v192
	v_cvt_pk_bf16_f32 v96, v210, v211
	v_cvt_pk_bf16_f32 v97, v212, v213
	v_cvt_pk_bf16_f32 v98, v214, v215
	v_cvt_pk_bf16_f32 v99, v216, v217
	v_cvt_pk_bf16_f32 v100, v218, v219
	s_waitcnt lgkmcnt(2)
	v_mfma_f32_32x32x16_bf16 v[112:127], v[160:163], v[132:135], v[112:127]
	v_cvt_pk_bf16_f32 v101, v220, v221
	v_cvt_pk_bf16_f32 v102, v222, v223
	v_cvt_pk_bf16_f32 v103, v224, v225
	v_cvt_pk_bf16_f32 v104, v251, v252
	v_cvt_pk_bf16_f32 v105, v253, v186
	v_cvt_pk_bf16_f32 v106, v188, v189
	s_waitcnt lgkmcnt(1)
	v_mfma_f32_32x32x16_bf16 v[80:95], v[164:167], v[132:135], v[80:95]
	ds_read_b128 v[160:163], v207 offset:32768
	ds_read_b128 v[164:167], v207 offset:40960
	v_cvt_pk_bf16_f32 v107, v190, v191
	v_cvt_pk_bf16_f32 v111, v174, v111
	v_permlane32_swap_b32_e32 v96, v98
	v_permlane32_swap_b32_e32 v97, v99
	v_permlane32_swap_b32_e32 v100, v102
	s_waitcnt lgkmcnt(1)
	v_mfma_f32_32x32x16_bf16 v[112:127], v[160:163], v[128:131], v[112:127]
	v_permlane32_swap_b32_e32 v101, v103
	v_permlane32_swap_b32_e32 v104, v106
	v_permlane32_swap_b32_e32 v105, v107
	v_permlane32_swap_b32_e32 v109, v111
	s_waitcnt lgkmcnt(0)
	v_mfma_f32_32x32x16_bf16 v[80:95], v[164:167], v[128:131], v[80:95]
	s_min_u32 s40, s2, 0xfc
	s_add_i32 s100, s40, 3
	s_mul_i32 s100, s100, 0x60000
	v_add_u32_e32 v254, s100, v14
	v_add_u32_e32 v255, s100, v15
	global_load_dwordx4 v[160:163], v254, s[58:59]
	global_load_dwordx4 v[164:167], v255, s[58:59]
	global_load_dwordx4 v[168:171], v254, s[8:9]
	global_load_dwordx4 v[172:175], v255, s[8:9]
	v_add_u32_e32 v255, vcc_hi, v208
	ds_read_b64_tr_b16 v[210:211], v255 offset:0
	ds_read_b64_tr_b16 v[212:213], v255 offset:0x800
	ds_read_b64_tr_b16 v[214:215], v255 offset:0x1000
	ds_read_b64_tr_b16 v[216:217], v255 offset:0x1800
	ds_read_b64_tr_b16 v[218:219], v255 offset:0x2000
	ds_read_b64_tr_b16 v[220:221], v255 offset:0x2800
	ds_read_b64_tr_b16 v[222:223], v255 offset:0x3000
	ds_read_b64_tr_b16 v[224:225], v255 offset:0x3800
	s_waitcnt lgkmcnt(0)
	s_nop 0
	v_mfma_f32_32x32x16_bf16 v[16:31], v[96:99], v[210:213], v[16:31]
	ds_read_b64_tr_b16 v[210:211], v255 offset:0x200
	ds_read_b64_tr_b16 v[212:213], v255 offset:0xa00
	v_mfma_f32_32x32x16_bf16 v[16:31], v[100:103], v[214:217], v[16:31]
	ds_read_b64_tr_b16 v[214:215], v255 offset:0x1200
	ds_read_b64_tr_b16 v[216:217], v255 offset:0x1a00
	v_mfma_f32_32x32x16_bf16 v[16:31], v[104:107], v[218:221], v[16:31]
	ds_read_b64_tr_b16 v[218:219], v255 offset:0x2200
	ds_read_b64_tr_b16 v[220:221], v255 offset:0x2a00
	v_mfma_f32_32x32x16_bf16 v[16:31], v[108:111], v[222:225], v[16:31]
	ds_read_b64_tr_b16 v[222:223], v255 offset:0x3200
	ds_read_b64_tr_b16 v[224:225], v255 offset:0x3a00
	s_waitcnt lgkmcnt(0)
	v_mfma_f32_32x32x16_bf16 v[32:47], v[96:99], v[210:213], v[32:47]
	ds_read_b64_tr_b16 v[210:211], v255 offset:0x400
	ds_read_b64_tr_b16 v[212:213], v255 offset:0xc00
	v_mfma_f32_32x32x16_bf16 v[32:47], v[100:103], v[214:217], v[32:47]
	ds_read_b64_tr_b16 v[214:215], v255 offset:0x1400
	ds_read_b64_tr_b16 v[216:217], v255 offset:0x1c00
	v_mfma_f32_32x32x16_bf16 v[32:47], v[104:107], v[218:221], v[32:47]
	ds_read_b64_tr_b16 v[218:219], v255 offset:0x2400
	ds_read_b64_tr_b16 v[220:221], v255 offset:0x2c00
	v_mfma_f32_32x32x16_bf16 v[32:47], v[108:111], v[222:225], v[32:47]
	ds_read_b64_tr_b16 v[222:223], v255 offset:0x3400
	ds_read_b64_tr_b16 v[224:225], v255 offset:0x3c00
	s_waitcnt lgkmcnt(0)
	v_mfma_f32_32x32x16_bf16 v[48:63], v[96:99], v[210:213], v[48:63]
	ds_read_b64_tr_b16 v[210:211], v255 offset:0x600
	ds_read_b64_tr_b16 v[212:213], v255 offset:0xe00
	v_mfma_f32_32x32x16_bf16 v[48:63], v[100:103], v[214:217], v[48:63]
	ds_read_b64_tr_b16 v[214:215], v255 offset:0x1600
	ds_read_b64_tr_b16 v[216:217], v255 offset:0x1e00
	v_mfma_f32_32x32x16_bf16 v[48:63], v[104:107], v[218:221], v[48:63]
	ds_read_b64_tr_b16 v[218:219], v255 offset:0x2600
	ds_read_b64_tr_b16 v[220:221], v255 offset:0x2e00
	v_mfma_f32_32x32x16_bf16 v[48:63], v[108:111], v[222:225], v[48:63]
	ds_read_b64_tr_b16 v[222:223], v255 offset:0x3600
	ds_read_b64_tr_b16 v[224:225], v255 offset:0x3e00
	s_waitcnt lgkmcnt(0)
	v_mfma_f32_32x32x16_bf16 v[64:79], v[96:99], v[210:213], v[64:79]
	v_exp_f32_e32 v210, v124
	v_exp_f32_e32 v213, v125
	v_exp_f32_e32 v211, v126
	v_exp_f32_e32 v212, v127
	v_mfma_f32_32x32x16_bf16 v[64:79], v[100:103], v[214:217], v[64:79]
	v_exp_f32_e32 v215, v120
	v_exp_f32_e32 v217, v121
	v_exp_f32_e32 v214, v122
	v_exp_f32_e32 v216, v123
	s_cmpk_gt_u32 s2, 0xfc
	v_mfma_f32_32x32x16_bf16 v[64:79], v[104:107], v[218:221], v[64:79]
	v_exp_f32_e32 v221, v114
	v_exp_f32_e32 v220, v116
	v_exp_f32_e32 v218, v118
	v_exp_f32_e32 v219, v119
	s_mov_b32 s100, vcc_lo
	s_mov_b32 vcc_lo, vcc_hi
	s_mov_b32 vcc_hi, s101
	s_mov_b32 s101, s100
	s_waitcnt lgkmcnt(0)
	s_barrier
; #define SBAR() __builtin_amdgcn_sched_barrier(0)
; #define RESC(a) do { if (!FIXED && __any((a) < 1.f)) { if (hi == 0) al_l[r32] = (a); asm volatile("s_waitcnt lgkmcnt(0)" ::: "memory"); \
;     _Pragma("unroll") for (int d = 0; d < 4; ++d) _Pragma("unroll") for (int r = 0; r < 16; ++r) o[d][r] *= al_l[crow(r, hi)]; } } while (0)
; #define MASK(P0, P1, t) do { if (BANDED) band_mask(P0, P1, rel00 + (t) * KVBLK, mlo, mhi); } while (0)
; __device__ __forceinline__ void qkt_c(f32x16& p0, f32x16& p1, const bf16* Ks, const bf16x8* qr, int r32, int hi) {
;   const f32x16 cinit = {};
; #pragma unroll
;   for (int d0 = 0; d0 < 8; ++d0) { int cb = (d0 * 16 + hi * 8) * 2;
;     bf16x8 b0 = *reinterpret_cast<const bf16x8*>((const char*)Ks + KSWZ(r32, cb));
;     bf16x8 b1 = *reinterpret_cast<const bf16x8*>((const char*)Ks + KSWZ(32 + r32, cb));
;     p0 = __builtin_amdgcn_mfma_f32_32x32x16_bf16(b0, qr[d0], d0 == 0 ? cinit : p0, 0, 0, 0);
;     p1 = __builtin_amdgcn_mfma_f32_32x32x16_bf16(b1, qr[d0], d0 == 0 ? cinit : p1, 0, 0, 0); }
; }
; template <bool BANDED, bool FIXED> ...
;     ...
;   }
;   SBAR(); if (FIXED) qkt_c(pB0, pB1, (bf16*)((char*)K_lds + SHM_K), qr, r32, hi); else qkt(pB0, pB1, (bf16*)((char*)K_lds + SHM_K), qr, r32, hi, 0.f); MASK(pB0, pB1, NT - 1);
;   finishSM(pA0, pA1, alA, l_reg, pa0, pa1, pa2, pa3); SBAR();
;   pv_d0(o, vb0, pa0, pa1, pa2, pa3); partialSM<FIXED, !BANDED>(pB0, pB1, m_reg, mnB, alB);
;   __syncthreads(); RESC(alB);
;   finishSM(pB0, pB1, alB, l_reg, pa0, pa1, pa2, pa3); SBAR();
	ds_read_b128 v[2:5], v200 offset:49152
	ds_read_b128 v[6:9], v200 offset:57344
	v_mfma_f32_32x32x16_bf16 v[64:79], v[108:111], v[222:225], v[64:79]
	v_exp_f32_e32 v223, v112
	v_exp_f32_e32 v225, v113
	v_exp_f32_e32 v224, v115
	v_exp_f32_e32 v222, v117
	s_cbranch_scc0 .LBB0_118
	v_mov_b32_e32 v186, 0x358637bd
	v_mov_b32_e32 v188, 0x3c0881c4
	v_mov_b32_e32 v189, 0xbab64f3b
	v_mov_b32_e32 v190, 1
	v_bfrev_b32_e32 v191, 0.5
	v_mov_b32_e32 v192, 0xf149f2ca
	v_mov_b32_e32 v193, 0xff800000
	v_add_u32_e32 v255, vcc_hi, v208
	v_add_u32_e32 v254, s101, v208
	v_exp_f32_e32 v12, v80
	v_exp_f32_e32 v13, v81
	v_exp_f32_e32 v14, v82
	s_waitcnt lgkmcnt(1)
	v_mfma_f32_32x32x16_bf16 v[112:127], v[2:5], v[156:159], 0
	v_exp_f32_e32 v15, v83
	v_exp_f32_e32 v80, v84
	v_exp_f32_e32 v81, v85
	v_exp_f32_e32 v82, v86
	v_exp_f32_e32 v83, v87
	v_exp_f32_e32 v84, v88
	v_exp_f32_e32 v85, v89
	s_waitcnt lgkmcnt(0)
	v_mfma_f32_32x32x16_bf16 v[96:111], v[6:9], v[156:159], 0
	ds_read_b128 v[2:5], v201 offset:49152
	ds_read_b128 v[6:9], v201 offset:57344
	v_exp_f32_e32 v86, v90
	v_exp_f32_e32 v87, v91
	v_exp_f32_e32 v88, v92
	v_exp_f32_e32 v89, v93
	v_exp_f32_e32 v90, v94
	v_exp_f32_e32 v91, v95
	s_waitcnt lgkmcnt(1)
	v_mfma_f32_32x32x16_bf16 v[112:127], v[2:5], v[152:155], v[112:127]
	v_cvt_pk_bf16_f32 v10, v210, v213
	v_cvt_pk_bf16_f32 v11, v211, v212
	s_waitcnt lgkmcnt(0)
	v_mfma_f32_32x32x16_bf16 v[96:111], v[6:9], v[152:155], v[96:111]
	ds_read_b128 v[2:5], v202 offset:49152
	ds_read_b128 v[6:9], v202 offset:57344
	s_waitcnt lgkmcnt(1)
	v_mfma_f32_32x32x16_bf16 v[112:127], v[2:5], v[148:151], v[112:127]
	s_waitcnt lgkmcnt(0)
	v_mfma_f32_32x32x16_bf16 v[96:111], v[6:9], v[148:151], v[96:111]
	ds_read_b128 v[2:5], v203 offset:49152
	ds_read_b128 v[6:9], v203 offset:57344
	s_waitcnt lgkmcnt(1)
	v_mfma_f32_32x32x16_bf16 v[112:127], v[2:5], v[144:147], v[112:127]
	s_waitcnt lgkmcnt(0)
	v_mfma_f32_32x32x16_bf16 v[96:111], v[6:9], v[144:147], v[96:111]
	ds_read_b128 v[2:5], v206 offset:49152
	ds_read_b128 v[6:9], v206 offset:57344
	s_waitcnt lgkmcnt(1)
	v_mfma_f32_32x32x16_bf16 v[112:127], v[2:5], v[140:143], v[112:127]
	s_waitcnt lgkmcnt(0)
	v_mfma_f32_32x32x16_bf16 v[96:111], v[6:9], v[140:143], v[96:111]
	ds_read_b128 v[2:5], v204 offset:49152
	ds_read_b128 v[6:9], v204 offset:57344
	s_waitcnt lgkmcnt(1)
	v_mfma_f32_32x32x16_bf16 v[112:127], v[2:5], v[136:139], v[112:127]
	s_waitcnt lgkmcnt(0)
	v_mfma_f32_32x32x16_bf16 v[96:111], v[6:9], v[136:139], v[96:111]
	ds_read_b128 v[2:5], v205 offset:49152
	ds_read_b128 v[6:9], v205 offset:57344
	s_waitcnt lgkmcnt(1)
	v_mfma_f32_32x32x16_bf16 v[112:127], v[2:5], v[132:135], v[112:127]
	s_waitcnt lgkmcnt(0)
	v_mfma_f32_32x32x16_bf16 v[96:111], v[6:9], v[132:135], v[96:111]
	ds_read_b128 v[2:5], v207 offset:49152
	ds_read_b128 v[6:9], v207 offset:57344
	s_waitcnt lgkmcnt(1)
	v_mfma_f32_32x32x16_bf16 v[112:127], v[2:5], v[128:131], v[112:127]
	v_add_f32_e32 v2, 0, v223
	v_add_f32_e32 v2, v225, v2
	v_add_f32_e32 v2, v221, v2
	v_add_f32_e32 v2, v224, v2
	v_add_f32_e32 v2, v220, v2
	v_add_f32_e32 v2, v222, v2
	v_add_f32_e32 v2, v218, v2
	v_add_f32_e32 v2, v219, v2
	v_add_f32_e32 v2, v215, v2
	v_add_f32_e32 v2, v217, v2
	v_add_f32_e32 v2, v214, v2
	v_add_f32_e32 v2, v216, v2
	v_add_f32_e32 v2, v210, v2
	v_add_f32_e32 v2, v213, v2
	v_add_f32_e32 v2, v211, v2
	v_add_f32_e32 v2, v212, v2
	v_add_f32_e32 v2, v12, v2
	v_add_f32_e32 v2, v13, v2
	v_add_f32_e32 v2, v14, v2
	v_add_f32_e32 v2, v15, v2
	v_add_f32_e32 v2, v80, v2
	v_add_f32_e32 v2, v81, v2
	v_add_f32_e32 v2, v82, v2
	v_add_f32_e32 v2, v83, v2
	v_add_f32_e32 v2, v84, v2
	v_add_f32_e32 v2, v85, v2
	v_add_f32_e32 v2, v86, v2
	v_add_f32_e32 v2, v87, v2
	v_add_f32_e32 v2, v88, v2
	v_add_f32_e32 v2, v89, v2
	v_add_f32_e32 v2, v90, v2
	v_add_f32_e32 v2, v91, v2
	s_waitcnt lgkmcnt(0)
	v_mfma_f32_32x32x16_bf16 v[96:111], v[6:9], v[128:131], v[96:111]
	v_mov_b32_e32 v3, v2
	v_cvt_pk_bf16_f32 v4, v223, v225
	v_cvt_pk_bf16_f32 v5, v221, v224
	v_cvt_pk_bf16_f32 v6, v220, v222
	v_cvt_pk_bf16_f32 v7, v218, v219
	s_nop 1
	v_permlane32_swap_b32_e32 v2, v3
	v_permlane32_swap_b32_e32 v4, v6
	v_permlane32_swap_b32_e32 v5, v7
	v_cvt_pk_bf16_f32 v8, v215, v217
	v_cvt_pk_bf16_f32 v9, v214, v216
	v_cvt_pk_bf16_f32 v12, v12, v13
	v_cvt_pk_bf16_f32 v13, v14, v15
	v_cvt_pk_bf16_f32 v14, v80, v81
	v_cvt_pk_bf16_f32 v15, v82, v83
	v_cvt_pk_bf16_f32 v80, v84, v85
	v_cvt_pk_bf16_f32 v81, v86, v87
	v_cvt_pk_bf16_f32 v82, v88, v89
	v_cvt_pk_bf16_f32 v83, v90, v91
	s_nop 0
	v_permlane32_swap_b32_e32 v8, v10
	v_permlane32_swap_b32_e32 v9, v11
	v_permlane32_swap_b32_e32 v12, v14
	v_permlane32_swap_b32_e32 v13, v15
	v_permlane32_swap_b32_e32 v80, v82
	v_permlane32_swap_b32_e32 v81, v83
	ds_read_b64_tr_b16 v[84:85], v255 offset:0
	ds_read_b64_tr_b16 v[86:87], v255 offset:0x800
	ds_read_b64_tr_b16 v[88:89], v255 offset:0x1000
	ds_read_b64_tr_b16 v[90:91], v255 offset:0x1800
	ds_read_b64_tr_b16 v[92:93], v255 offset:0x2000
	ds_read_b64_tr_b16 v[94:95], v255 offset:0x2800
	ds_read_b64_tr_b16 v[128:129], v255 offset:0x3000
	ds_read_b64_tr_b16 v[130:131], v255 offset:0x3800
	s_waitcnt lgkmcnt(0)
	s_nop 0
	v_mfma_f32_32x32x16_bf16 v[16:31], v[4:7], v[84:87], v[16:31]
	ds_read_b64_tr_b16 v[84:85], v255 offset:0x200
	ds_read_b64_tr_b16 v[86:87], v255 offset:0xa00
	v_mfma_f32_32x32x16_bf16 v[16:31], v[8:11], v[88:91], v[16:31]
	ds_read_b64_tr_b16 v[88:89], v255 offset:0x1200
	ds_read_b64_tr_b16 v[90:91], v255 offset:0x1a00
	v_mfma_f32_32x32x16_bf16 v[16:31], v[12:15], v[92:95], v[16:31]
	ds_read_b64_tr_b16 v[92:93], v255 offset:0x2200
	ds_read_b64_tr_b16 v[94:95], v255 offset:0x2a00
	v_mfma_f32_32x32x16_bf16 v[16:31], v[80:83], v[128:131], v[16:31]
	ds_read_b64_tr_b16 v[128:129], v255 offset:0x3200
	ds_read_b64_tr_b16 v[130:131], v255 offset:0x3a00
	s_waitcnt lgkmcnt(0)
; #define SBAR() __builtin_amdgcn_sched_barrier(0)
; __device__ __forceinline__ void finishSM(f32x16& p0, f32x16& p1, float alpha, float& l_reg, bf16x8& pa0, bf16x8& pa1, bf16x8& pa2, bf16x8& pa3) {
; #pragma unroll
;   for (int r = 0; r < 16; ++r) p1[r] = __builtin_amdgcn_exp2f(p1[r]);
;   float ps = 0;
; #pragma unroll
;   for (int r = 0; r < 16; ++r) ps += p0[r];
; #pragma unroll
;   for (int r = 0; r < 16; ++r) ps += p1[r];
;   { auto rr = __builtin_amdgcn_permlane32_swap(__float_as_uint(ps), __float_as_uint(ps), false, false);
;     ps = __uint_as_float(rr[0]) + __uint_as_float(rr[1]); }
;   l_reg = l_reg * alpha + ps;
;     ...
;   PK4(p0, 0, pa0); PK4(p0, 8, pa1); PK4(p1, 0, pa2); PK4(p1, 8, pa3);
; template <int D0> __device__ __forceinline__ void pv_one(f32x16& od, int vb, bf16x8 pa0, bf16x8 pa1, bf16x8 pa2, bf16x8 pa3) {
;   const s16x4 l0 = tr_read<v_rd_off(D0, 0, 0)>(vb), h0 = tr_read<v_rd_off(D0, 0, 1)>(vb), l1 = tr_read<v_rd_off(D0, 1, 0)>(vb), h1 = tr_read<v_rd_off(D0, 1, 1)>(vb);
;   const s16x4 l2 = tr_read<v_rd_off(D0, 2, 0)>(vb), h2 = tr_read<v_rd_off(D0, 2, 1)>(vb), l3 = tr_read<v_rd_off(D0, 3, 0)>(vb), h3 = tr_read<v_rd_off(D0, 3, 1)>(vb);
;   asm volatile("s_waitcnt lgkmcnt(0)" ::: "memory"); SBAR();
;     ...
;   od = __builtin_amdgcn_mfma_f32_32x32x16_bf16(pa0, PK(l0, h0), od, 0, 0, 0);
;   od = __builtin_amdgcn_mfma_f32_32x32x16_bf16(pa1, PK(l1, h1), od, 0, 0, 0);
;   od = __builtin_amdgcn_mfma_f32_32x32x16_bf16(pa2, PK(l2, h2), od, 0, 0, 0);
;   od = __builtin_amdgcn_mfma_f32_32x32x16_bf16(pa3, PK(l3, h3), od, 0, 0, 0);
;     ...
; }
; __device__ __forceinline__ void pv_d0(f32x16* o, int vb, bf16x8 pa0, bf16x8 pa1, bf16x8 pa2, bf16x8 pa3) {
;   pv_one<0>(o[0], vb, pa0, pa1, pa2, pa3); pv_one<1>(o[1], vb, pa0, pa1, pa2, pa3); pv_one<2>(o[2], vb, pa0, pa1, pa2, pa3); pv_one<3>(o[3], vb, pa0, pa1, pa2, pa3);
	v_mfma_f32_32x32x16_bf16 v[32:47], v[4:7], v[84:87], v[32:47]
	ds_read_b64_tr_b16 v[84:85], v255 offset:0x400
	ds_read_b64_tr_b16 v[86:87], v255 offset:0xc00
	v_mfma_f32_32x32x16_bf16 v[32:47], v[8:11], v[88:91], v[32:47]
	ds_read_b64_tr_b16 v[88:89], v255 offset:0x1400
	ds_read_b64_tr_b16 v[90:91], v255 offset:0x1c00
	v_mfma_f32_32x32x16_bf16 v[32:47], v[12:15], v[92:95], v[32:47]
	ds_read_b64_tr_b16 v[92:93], v255 offset:0x2400
	ds_read_b64_tr_b16 v[94:95], v255 offset:0x2c00
	v_mfma_f32_32x32x16_bf16 v[32:47], v[80:83], v[128:131], v[32:47]
	ds_read_b64_tr_b16 v[128:129], v255 offset:0x3400
	ds_read_b64_tr_b16 v[130:131], v255 offset:0x3c00
	s_waitcnt lgkmcnt(0)
	v_mfma_f32_32x32x16_bf16 v[48:63], v[4:7], v[84:87], v[48:63]
	ds_read_b64_tr_b16 v[84:85], v255 offset:0x600
	ds_read_b64_tr_b16 v[86:87], v255 offset:0xe00
	v_mfma_f32_32x32x16_bf16 v[48:63], v[8:11], v[88:91], v[48:63]
	ds_read_b64_tr_b16 v[88:89], v255 offset:0x1600
	ds_read_b64_tr_b16 v[90:91], v255 offset:0x1e00
	v_mfma_f32_32x32x16_bf16 v[48:63], v[12:15], v[92:95], v[48:63]
	ds_read_b64_tr_b16 v[92:93], v255 offset:0x2600
	ds_read_b64_tr_b16 v[94:95], v255 offset:0x2e00
	v_mfma_f32_32x32x16_bf16 v[48:63], v[80:83], v[128:131], v[48:63]
	ds_read_b64_tr_b16 v[128:129], v255 offset:0x3600
	ds_read_b64_tr_b16 v[130:131], v255 offset:0x3e00
	s_waitcnt lgkmcnt(0)
	v_mfma_f32_32x32x16_bf16 v[64:79], v[4:7], v[84:87], v[64:79]
	v_exp_f32_e32 v6, v112
	v_exp_f32_e32 v7, v113
	v_exp_f32_e32 v84, v126
	v_exp_f32_e32 v85, v127
	v_add_f32_e32 v4, 0, v6
	v_add_f32_e32 v4, v7, v4
	v_exp_f32_e32 v86, v96
	v_mfma_f32_32x32x16_bf16 v[64:79], v[8:11], v[88:91], v[64:79]
	v_exp_f32_e32 v8, v114
	v_exp_f32_e32 v9, v115
	v_exp_f32_e32 v10, v116
	v_exp_f32_e32 v11, v117
	v_add_f32_e32 v4, v8, v4
	v_add_f32_e32 v4, v9, v4
	v_add_f32_e32 v4, v10, v4
	v_mfma_f32_32x32x16_bf16 v[64:79], v[12:15], v[92:95], v[64:79]
	v_exp_f32_e32 v12, v118
	v_exp_f32_e32 v13, v119
	v_exp_f32_e32 v14, v120
	v_exp_f32_e32 v15, v121
	v_add_f32_e32 v4, v11, v4
	v_add_f32_e32 v4, v12, v4
	v_add_f32_e32 v4, v13, v4
	v_mfma_f32_32x32x16_bf16 v[64:79], v[80:83], v[128:131], v[64:79]
	v_exp_f32_e32 v80, v122
	v_exp_f32_e32 v81, v123
	v_exp_f32_e32 v82, v124
	v_add_f32_e32 v4, v14, v4
	v_exp_f32_e32 v83, v125
	v_add_f32_e32 v4, v15, v4
	v_add_f32_e32 v4, v80, v4
	v_add_f32_e32 v4, v81, v4
	v_add_f32_e32 v4, v82, v4
	v_exp_f32_e32 v87, v97
	v_add_f32_e32 v4, v83, v4
	v_exp_f32_e32 v88, v98
	v_add_f32_e32 v4, v84, v4
	v_exp_f32_e32 v89, v99
	v_add_f32_e32 v4, v85, v4
	v_exp_f32_e32 v90, v100
	v_add_f32_e32 v4, v86, v4
	v_exp_f32_e32 v91, v101
	v_add_f32_e32 v4, v87, v4
	v_exp_f32_e32 v92, v102
	v_add_f32_e32 v4, v88, v4
	v_exp_f32_e32 v93, v103
	v_add_f32_e32 v4, v89, v4
	v_exp_f32_e32 v94, v104
	v_add_f32_e32 v4, v90, v4
	v_exp_f32_e32 v95, v105
	v_add_f32_e32 v4, v91, v4
	v_exp_f32_e32 v96, v106
	v_add_f32_e32 v4, v92, v4
	v_exp_f32_e32 v97, v107
	v_add_f32_e32 v4, v93, v4
	v_exp_f32_e32 v98, v108
	v_add_f32_e32 v4, v94, v4
	v_exp_f32_e32 v99, v109
	v_add_f32_e32 v4, v95, v4
	v_exp_f32_e32 v100, v110
	v_add_f32_e32 v4, v96, v4
	v_exp_f32_e32 v101, v111
	v_add_f32_e32 v4, v97, v4
	v_add_f32_e32 v4, v98, v4
	v_add_f32_e32 v4, v99, v4
	v_add_f32_e32 v4, v100, v4
	v_add_f32_e32 v4, v101, v4
	v_mov_b32_e32 v5, v4
	s_nop 1
	v_permlane32_swap_b32_e32 v4, v5
	v_cvt_pk_bf16_f32 v6, v6, v7
	v_cvt_pk_bf16_f32 v7, v8, v9
	v_cvt_pk_bf16_f32 v8, v10, v11
	v_cvt_pk_bf16_f32 v9, v12, v13
	v_cvt_pk_bf16_f32 v10, v14, v15
	v_cvt_pk_bf16_f32 v11, v80, v81
	v_cvt_pk_bf16_f32 v12, v82, v83
	v_cvt_pk_bf16_f32 v13, v84, v85
	v_cvt_pk_bf16_f32 v80, v86, v87
	v_cvt_pk_bf16_f32 v81, v88, v89
	v_cvt_pk_bf16_f32 v82, v90, v91
	v_cvt_pk_bf16_f32 v83, v92, v93
	v_cvt_pk_bf16_f32 v84, v94, v95
	v_cvt_pk_bf16_f32 v85, v96, v97
	v_cvt_pk_bf16_f32 v86, v98, v99
	v_cvt_pk_bf16_f32 v87, v100, v101
	s_barrier
	v_permlane32_swap_b32_e32 v6, v8
	v_permlane32_swap_b32_e32 v7, v9
	v_permlane32_swap_b32_e32 v10, v12
	v_permlane32_swap_b32_e32 v11, v13
	v_permlane32_swap_b32_e32 v80, v82
	v_permlane32_swap_b32_e32 v81, v83
	v_permlane32_swap_b32_e32 v84, v86
	v_permlane32_swap_b32_e32 v85, v87
	ds_read_b64_tr_b16 v[88:89], v254 offset:0
	ds_read_b64_tr_b16 v[90:91], v254 offset:0x800
	ds_read_b64_tr_b16 v[92:93], v254 offset:0x1000
	ds_read_b64_tr_b16 v[94:95], v254 offset:0x1800
	ds_read_b64_tr_b16 v[96:97], v254 offset:0x2000
	ds_read_b64_tr_b16 v[98:99], v254 offset:0x2800
	ds_read_b64_tr_b16 v[100:101], v254 offset:0x3000
	ds_read_b64_tr_b16 v[102:103], v254 offset:0x3800
	s_waitcnt lgkmcnt(0)
	s_nop 0
	v_mfma_f32_32x32x16_bf16 v[16:31], v[6:9], v[88:91], v[16:31]
	ds_read_b64_tr_b16 v[88:89], v254 offset:0x200
	ds_read_b64_tr_b16 v[90:91], v254 offset:0xa00
	v_mfma_f32_32x32x16_bf16 v[16:31], v[10:13], v[92:95], v[16:31]
	ds_read_b64_tr_b16 v[92:93], v254 offset:0x1200
	ds_read_b64_tr_b16 v[94:95], v254 offset:0x1a00
	v_mfma_f32_32x32x16_bf16 v[16:31], v[80:83], v[96:99], v[16:31]
	ds_read_b64_tr_b16 v[96:97], v254 offset:0x2200
	ds_read_b64_tr_b16 v[98:99], v254 offset:0x2a00
	v_mfma_f32_32x32x16_bf16 v[16:31], v[84:87], v[100:103], v[16:31]
	ds_read_b64_tr_b16 v[100:101], v254 offset:0x3200
	ds_read_b64_tr_b16 v[102:103], v254 offset:0x3a00
	s_waitcnt lgkmcnt(0)
	v_mfma_f32_32x32x16_bf16 v[32:47], v[6:9], v[88:91], v[32:47]
	ds_read_b64_tr_b16 v[88:89], v254 offset:0x400
	ds_read_b64_tr_b16 v[90:91], v254 offset:0xc00
	v_mfma_f32_32x32x16_bf16 v[32:47], v[10:13], v[92:95], v[32:47]
	ds_read_b64_tr_b16 v[92:93], v254 offset:0x1400
	ds_read_b64_tr_b16 v[94:95], v254 offset:0x1c00
	v_mfma_f32_32x32x16_bf16 v[32:47], v[80:83], v[96:99], v[32:47]
	ds_read_b64_tr_b16 v[96:97], v254 offset:0x2400
	ds_read_b64_tr_b16 v[98:99], v254 offset:0x2c00
	v_mfma_f32_32x32x16_bf16 v[32:47], v[84:87], v[100:103], v[32:47]
	ds_read_b64_tr_b16 v[100:101], v254 offset:0x3400
	ds_read_b64_tr_b16 v[102:103], v254 offset:0x3c00
	s_waitcnt lgkmcnt(0)
	v_mfma_f32_32x32x16_bf16 v[48:63], v[6:9], v[88:91], v[48:63]
	ds_read_b64_tr_b16 v[88:89], v254 offset:0x600
	ds_read_b64_tr_b16 v[90:91], v254 offset:0xe00
	v_mfma_f32_32x32x16_bf16 v[48:63], v[10:13], v[92:95], v[48:63]
	ds_read_b64_tr_b16 v[92:93], v254 offset:0x1600
	ds_read_b64_tr_b16 v[94:95], v254 offset:0x1e00
	v_mfma_f32_32x32x16_bf16 v[48:63], v[80:83], v[96:99], v[48:63]
	ds_read_b64_tr_b16 v[96:97], v254 offset:0x2600
	ds_read_b64_tr_b16 v[98:99], v254 offset:0x2e00
	v_mfma_f32_32x32x16_bf16 v[48:63], v[84:87], v[100:103], v[48:63]
	ds_read_b64_tr_b16 v[100:101], v254 offset:0x3600
	ds_read_b64_tr_b16 v[102:103], v254 offset:0x3e00
	s_waitcnt lgkmcnt(0)
	v_mfma_f32_32x32x16_bf16 v[64:79], v[6:9], v[88:91], v[64:79]
	s_and_b64 vcc, exec, s[22:23]
	v_mfma_f32_32x32x16_bf16 v[64:79], v[10:13], v[92:95], v[64:79]
	v_mfma_f32_32x32x16_bf16 v[64:79], v[80:83], v[96:99], v[64:79]
	v_mfma_f32_32x32x16_bf16 v[64:79], v[84:87], v[100:103], v[64:79]
	s_cbranch_vccz .LBB0_121
	s_setprio 0
